# NA grid-row tile loop: K/V tiles staged by LDS-DMA into a 4-slot LDS ring three tiles ahead (replaces register-staged loads with one tile of lead)
# baseline (speedup 1.0000x reference)
.LBB0_160:
	s_andn2_b64 vcc, exec, s[4:5]
	s_cbranch_vccnz .LBB0_267
	s_cmp_eq_u32 s81, 0
	s_movk_i32 s2, 0x800
	s_cselect_b32 s69, s2, 0x840
	s_cmp_ge_i32 s72, s69
	s_cbranch_scc1 .LBB0_267
	v_ashrrev_i32_e32 v7, 1, v178
	s_movk_i32 s2, 0xffe0
	v_bfi_b32 v4, s2, v7, v178
	v_ashrrev_i32_e32 v5, 31, v4
	v_lshlrev_b32_e32 v3, 3, v178
	v_lshlrev_b64 v[110:111], 13, v[4:5]
	v_ashrrev_i32_e32 v114, 3, v178
	v_ashrrev_i32_e32 v118, 5, v178
	v_bfe_u32 v4, v3, 5, 1
	s_mov_b32 s2, 0x7ffffe
	v_and_or_b32 v4, v118, s2, v4
	v_lshlrev_b32_e32 v5, 5, v114
	v_and_b32_e32 v8, 24, v3
	s_movk_i32 s2, 0xe0
	v_and_or_b32 v5, v5, s2, v8
	s_add_u32 s89, s98, 0x4600000
	v_and_b32_e32 v116, 56, v3
	v_lshlrev_b32_e32 v4, 9, v4
	v_lshlrev_b32_e32 v5, 1, v5
	s_addc_u32 s26, s99, 0
	v_add3_u32 v113, 16, v4, v5
	v_lshlrev_b32_e32 v5, 1, v116
	v_lshlrev_b32_e32 v8, 4, v114
	s_movk_i32 s2, 0x70
	s_add_u32 s27, s98, 0x4600800
	v_lshlrev_b32_e32 v4, 7, v114
	v_bitop3_b32 v5, v5, v8, s2 bitop3:0x78
	s_addc_u32 s28, s99, 0
	v_add3_u32 v117, 16, v5, v4
	v_lshlrev_b32_e32 v4, 1, v178
	s_add_u32 s29, s98, 0x4601000
	v_bfe_u32 v6, v178, 5, 1
	v_and_b32_e32 v4, 32, v4
	s_movk_i32 s4, 0x118
	s_addc_u32 s36, s99, 0
	v_and_or_b32 v3, v3, s4, v4
	v_lshlrev_b32_e32 v4, 4, v178
	v_lshlrev_b32_e32 v119, 4, v6
	v_and_b32_e32 v0, 0x3fffffc0, v178
	v_and_b32_e32 v8, 0x70, v4
	v_bitop3_b32 v130, v119, v4, s2 bitop3:0x78
	s_movk_i32 s2, 0x60
	s_cmp_lg_u32 16, -1
	v_lshl_add_u32 v109, v0, 2, 16
	v_and_b32_e32 v0, 63, v178
	v_and_b32_e32 v2, 0xffffffe0, v7
	v_and_b32_e32 v5, 0xc0, v4
	v_bitop3_b32 v133, v119, v8, s2 bitop3:0x36
	s_cselect_b32 s2, 16, 0
	v_and_b32_e32 v108, 31, v178
	v_cmp_gt_u32_e64 s[76:77], 32, v0
	v_add3_u32 v135, v5, s2, v3
	v_ashrrev_i32_e32 v3, 31, v2
	v_and_b32_e32 v0, 32, v7
	v_writelane_b32 v254, s34, 18
	v_lshlrev_b64 v[120:121], 13, v[2:3]
	v_or_b32_e32 v2, v0, v108
	v_writelane_b32 v254, s35, 19
	s_lshl_b64 s[4:5], 1, s47
	v_cmp_ne_u32_e64 s[8:9], 31, v108
	v_med3_u32 v2, v2, 8, 56
	v_lshlrev_b32_e32 v5, 2, v6
	v_lshlrev_b32_e32 v112, 3, v6
	s_and_b32 s92, s4, 0xfff72ef6
	v_lshlrev_b32_e32 v122, 15, v6
	v_writelane_b32 v254, s8, 20
	v_add_u32_e32 v3, -8, v2
	v_add_u32_e32 v4, 8, v2
	v_subrev_u32_e32 v2, 24, v2
	v_or_b32_e32 v6, 32, v5
	s_cmp_lg_u64 s[92:93], 0
	v_writelane_b32 v254, s9, 21
	v_cmp_ge_u32_e32 vcc, v6, v3
	v_cmp_lt_i32_e64 s[8:9], v5, v2
	s_cselect_b64 s[6:7], -1, 0
	s_and_b64 s[8:9], vcc, s[8:9]
	v_writelane_b32 v254, s8, 22
	v_or_b32_e32 v6, 1, v5
	v_or_b32_e32 v7, 33, v5
	v_writelane_b32 v254, s9, 23
	v_cmp_lt_u32_e64 s[8:9], v6, v3
	v_cmp_ge_u32_e32 vcc, v7, v3
	v_cmp_lt_i32_e64 s[14:15], v6, v2
	v_writelane_b32 v254, s8, 24
	v_or_b32_e32 v6, 34, v5
	v_or_b32_e32 v7, 2, v5
	v_writelane_b32 v254, s9, 25
	v_cmp_lt_u32_e64 s[8:9], v5, v3
	v_cmp_lt_i32_e64 s[16:17], v7, v2
	v_bitop3_b32 v131, v119, v8, 32 bitop3:0x36
	v_writelane_b32 v254, s8, 26
	v_bitop3_b32 v132, v119, v8, 64 bitop3:0x36
	v_or_b32_e32 v8, 35, v5
	v_writelane_b32 v254, s9, 27
	s_and_b64 s[8:9], vcc, s[14:15]
	v_writelane_b32 v254, s8, 28
	v_cmp_ge_u32_e32 vcc, v6, v3
	v_or_b32_e32 v6, 3, v5
	v_writelane_b32 v254, s9, 29
	s_and_b64 s[8:9], vcc, s[16:17]
	v_writelane_b32 v254, s8, 30
	v_cmp_ge_u32_e32 vcc, v8, v3
	v_cmp_lt_i32_e64 s[22:23], v6, v2
	v_writelane_b32 v254, s9, 31
	v_cmp_lt_u32_e64 s[8:9], v6, v3
	v_or_b32_e32 v8, 40, v5
	v_or_b32_e32 v9, 8, v5
	v_writelane_b32 v254, s8, 32
	v_cmp_lt_i32_e64 s[24:25], v9, v2
	v_or_b32_e32 v10, 41, v5
	v_writelane_b32 v254, s9, 33
	v_cmp_lt_u32_e64 s[8:9], v7, v3
	v_or_b32_e32 v11, 10, v5
	v_cmp_lt_i32_e64 s[34:35], v11, v2
	v_writelane_b32 v254, s8, 34
	v_or_b32_e32 v12, 43, v5
	v_or_b32_e32 v13, 16, v5
	v_writelane_b32 v254, s9, 35
	s_and_b64 s[8:9], vcc, s[22:23]
	v_writelane_b32 v254, s8, 36
	v_cmp_ge_u32_e32 vcc, v8, v3
	v_or_b32_e32 v8, 9, v5
	v_writelane_b32 v254, s9, 37
	s_and_b64 s[8:9], vcc, s[24:25]
	v_writelane_b32 v254, s8, 38
	v_cmp_ge_u32_e32 vcc, v10, v3
	v_cmp_lt_i32_e64 s[30:31], v8, v2
	v_writelane_b32 v254, s9, 39
	v_cmp_lt_u32_e64 s[8:9], v8, v3
	v_or_b32_e32 v10, 42, v5
	v_cmp_lt_u32_e64 s[42:43], v13, v4
	v_writelane_b32 v254, s8, 40
	v_or_b32_e32 v15, 18, v5
	v_or_b32_e32 v14, 19, v5
	v_writelane_b32 v254, s9, 41
	v_cmp_lt_u32_e64 s[8:9], v9, v3
	v_cmp_lt_u32_e64 s[50:51], v15, v4
	v_cmp_lt_u32_e64 s[52:53], v14, v4
	v_writelane_b32 v254, s8, 42
	v_or_b32_e32 v17, 24, v5
	v_or_b32_e32 v16, 25, v5
	v_writelane_b32 v254, s9, 43
	s_and_b64 s[8:9], vcc, s[30:31]
	v_writelane_b32 v254, s8, 44
	v_cmp_ge_u32_e32 vcc, v10, v3
	v_or_b32_e32 v10, 11, v5
	v_writelane_b32 v254, s9, 45
	s_and_b64 s[8:9], vcc, s[34:35]
	v_writelane_b32 v254, s8, 46
	v_cmp_ge_u32_e32 vcc, v12, v3
	v_cmp_lt_i32_e64 s[40:41], v10, v2
	v_writelane_b32 v254, s9, 47
	v_cmp_lt_u32_e64 s[8:9], v10, v3
	v_or_b32_e32 v12, 17, v5
	v_cmp_lt_u32_e64 s[44:45], v12, v4
	v_writelane_b32 v254, s8, 48
	v_cmp_lt_u32_e64 s[58:59], v17, v4
	v_cmp_lt_u32_e64 s[60:61], v16, v4
	v_writelane_b32 v254, s9, 49
	v_cmp_lt_u32_e64 s[8:9], v11, v3
	v_or_b32_e32 v18, 26, v5
	v_cmp_lt_u32_e64 s[66:67], v18, v4
	v_writelane_b32 v254, s8, 50
	v_cmp_lt_i32_e64 s[22:23], v18, v2
	v_cmp_lt_i32_e64 s[10:11], v12, v2
	v_writelane_b32 v254, s9, 51
	s_and_b64 s[8:9], vcc, s[40:41]
	v_writelane_b32 v254, s8, 52
	v_cmp_ge_u32_e32 vcc, v13, v3
	v_cmp_lt_i32_e64 s[12:13], v13, v2
	v_writelane_b32 v254, s9, 53
	s_and_b64 s[8:9], vcc, s[42:43]
	v_cmp_ge_u32_e32 vcc, v12, v3
	s_and_b64 s[44:45], vcc, s[44:45]
	v_cmp_ge_u32_e32 vcc, v15, v3
	s_and_b64 s[50:51], vcc, s[50:51]
	v_cmp_ge_u32_e32 vcc, v14, v3
	s_and_b64 s[52:53], vcc, s[52:53]
	v_cmp_ge_u32_e32 vcc, v17, v3
	s_and_b64 s[58:59], vcc, s[58:59]
	v_cmp_ge_u32_e32 vcc, v16, v3
	s_and_b64 s[60:61], vcc, s[60:61]
	v_cmp_ge_u32_e32 vcc, v18, v3
	v_or_b32_e32 v18, 27, v5
	v_cmp_lt_i32_e64 s[14:15], v14, v2
	v_cmp_lt_i32_e64 s[16:17], v15, v2
	v_cmp_lt_i32_e64 s[18:19], v16, v2
	v_cmp_lt_i32_e64 s[20:21], v17, v2
	v_cmp_lt_i32_e64 s[30:31], v18, v2
	v_sub_u32_e32 v2, v5, v108
	v_sub_u32_e32 v2, v2, v0
	s_and_b64 s[66:67], vcc, s[66:67]
	v_cmp_ge_u32_e32 vcc, v18, v3
	v_add_u32_e32 v3, 59, v2
	v_min_i32_e32 v3, 15, v3
	v_lshlrev_b32_e32 v140, 2, v3
	v_and_b32_e32 v3, 0xffffff80, v178
	v_sub_u32_e32 v141, 16, v3
	v_add_u32_e32 v3, 27, v2
	v_med3_i32 v3, v3, -15, 15
	v_lshlrev_b32_e32 v142, 2, v3
	v_add_u32_e32 v3, 58, v2
	v_min_i32_e32 v3, 15, v3
	v_lshlrev_b32_e32 v143, 2, v3
	v_add_u32_e32 v3, 26, v2
	v_med3_i32 v3, v3, -15, 15
	v_lshlrev_b32_e32 v144, 2, v3
	v_add_u32_e32 v3, 57, v2
	v_min_i32_e32 v3, 15, v3
	v_lshlrev_b32_e32 v145, 2, v3
	v_sub_u32_e32 v3, v16, v108
	v_sub_u32_e32 v3, v3, v0
	v_med3_i32 v3, v3, -15, 15
	v_lshlrev_b32_e32 v146, 2, v3
	v_add_u32_e32 v3, 56, v2
	v_min_i32_e32 v3, 15, v3
	v_lshlrev_b32_e32 v147, 2, v3
	v_sub_u32_e32 v3, v17, v108
	v_sub_u32_e32 v3, v3, v0
	v_med3_i32 v3, v3, -15, 15
	v_lshlrev_b32_e32 v148, 2, v3
	v_add_u32_e32 v3, 51, v2
	v_min_i32_e32 v3, 15, v3
	v_lshlrev_b32_e32 v149, 2, v3
	v_sub_u32_e32 v3, v14, v108
	v_sub_u32_e32 v3, v3, v0
	v_med3_i32 v3, v3, -15, 15
	v_lshlrev_b32_e32 v150, 2, v3
	v_add_u32_e32 v3, 50, v2
	v_min_i32_e32 v3, 15, v3
	v_lshlrev_b32_e32 v151, 2, v3
	v_sub_u32_e32 v3, v15, v108
	v_sub_u32_e32 v3, v3, v0
	v_med3_i32 v3, v3, -15, 15
	v_lshlrev_b32_e32 v152, 2, v3
	v_add_u32_e32 v3, 49, v2
	v_min_i32_e32 v3, 15, v3
	v_lshlrev_b32_e32 v153, 2, v3
	v_sub_u32_e32 v3, v12, v108
	v_sub_u32_e32 v3, v3, v0
	v_med3_i32 v3, v3, -15, 15
	v_lshlrev_b32_e32 v154, 2, v3
	v_add_u32_e32 v3, 48, v2
	v_min_i32_e32 v3, 15, v3
	v_lshlrev_b32_e32 v155, 2, v3
	v_sub_u32_e32 v3, v13, v108
	v_sub_u32_e32 v3, v3, v0
	v_med3_i32 v3, v3, -15, 15
	v_lshlrev_b32_e32 v156, 2, v3
	v_add_u32_e32 v3, 43, v2
	v_med3_i32 v3, v3, -15, 15
	v_lshlrev_b32_e32 v157, 2, v3
	v_sub_u32_e32 v3, v10, v108
	v_sub_u32_e32 v3, v3, v0
	v_max_i32_e32 v3, -15, v3
	v_lshlrev_b32_e32 v158, 2, v3
	v_add_u32_e32 v3, 42, v2
	v_med3_i32 v3, v3, -15, 15
	v_lshlrev_b32_e32 v159, 2, v3
	v_sub_u32_e32 v3, v11, v108
	v_sub_u32_e32 v3, v3, v0
	v_max_i32_e32 v3, -15, v3
	v_lshlrev_b32_e32 v160, 2, v3
	v_add_u32_e32 v3, 41, v2
	v_med3_i32 v3, v3, -15, 15
	v_lshlrev_b32_e32 v161, 2, v3
	v_sub_u32_e32 v3, v8, v108
	v_sub_u32_e32 v3, v3, v0
	v_max_i32_e32 v3, -15, v3
	v_lshlrev_b32_e32 v162, 2, v3
	v_add_u32_e32 v3, 40, v2
	v_med3_i32 v3, v3, -15, 15
	v_lshlrev_b32_e32 v163, 2, v3
	v_sub_u32_e32 v3, v9, v108
	v_sub_u32_e32 v3, v3, v0
	v_max_i32_e32 v3, -15, v3
	v_lshlrev_b32_e32 v164, 2, v3
	v_add_u32_e32 v3, 35, v2
	v_med3_i32 v3, v3, -15, 15
	v_lshlrev_b32_e32 v165, 2, v3
	v_sub_u32_e32 v3, v6, v108
	v_sub_u32_e32 v3, v3, v0
	v_max_i32_e32 v3, -15, v3
	v_lshlrev_b32_e32 v166, 2, v3
	v_add_u32_e32 v3, 34, v2
	v_med3_i32 v3, v3, -15, 15
	v_lshlrev_b32_e32 v167, 2, v3
	v_sub_u32_e32 v3, v7, v108
	v_sub_u32_e32 v0, v3, v0
	v_max_i32_e32 v0, -15, v0
	v_lshlrev_b32_e32 v168, 2, v0
	v_add_u32_e32 v0, 33, v2
	v_med3_i32 v0, v0, -15, 15
	v_lshlrev_b32_e32 v169, 2, v0
	v_add_u32_e32 v0, 1, v2
	v_max_i32_e32 v0, -15, v0
	v_lshlrev_b32_e32 v170, 2, v0
	v_add_u32_e32 v0, 32, v2
	v_writelane_b32 v254, s8, 54
	v_med3_i32 v0, v0, -15, 15
	s_movk_i32 s2, 0x1e0
	v_writelane_b32 v254, s9, 55
	v_cmp_lt_u32_e64 s[70:71], v18, v4
	v_lshlrev_b32_e32 v171, 2, v0
	v_max_i32_e32 v0, -15, v2
	v_ashrrev_i32_e32 v115, 31, v114
	v_lshl_add_u32 v134, v108, 2, v109
	v_lshl_add_u32 v136, v108, 7, 16
	v_ashrrev_i32_e32 v179, 31, v178
	v_mov_b32_e32 v123, v1
	v_cmp_gt_i32_e64 s[4:5], s2, v178
	v_lshl_add_u32 v137, v178, 2, 16
	v_ashrrev_i32_e32 v138, 7, v178
	s_mov_b32 s43, 0x14000
	s_movk_i32 s42, 0x2000
	s_and_b64 s[70:71], vcc, s[70:71]
	v_add_u32_e32 v139, 0x2000, v135
	v_lshlrev_b32_e32 v172, 2, v0
	v_readlane_b32 s37, v254, 7
	s_mov_b32 s2, s72
	v_and_b32_e32 v2, 63, v178
	v_lshrrev_b32_e32 v3, 6, v178
	v_lshrrev_b32_e32 v4, 3, v2
	s_nop 0
	v_readfirstlane_b32 s32, v3
	v_lshlrev_b32_e32 v3, 16, v3
	v_and_b32_e32 v5, 7, v2
	v_xor_b32_e32 v5, v5, v4
	v_lshlrev_b32_e32 v5, 4, v5
	v_lshl_add_u32 v5, v4, 13, v5
	v_add_u32_e32 v220, v3, v5
	v_and_b32_e32 v4, 31, v2
	v_lshrrev_b32_e32 v4, 2, v4
	v_lshrrev_b32_e32 v5, 5, v2
	v_lshlrev_b32_e32 v5, 6, v5
	v_lshl_add_u32 v5, v4, 13, v5
	v_and_b32_e32 v4, 3, v2
	v_lshl_add_u32 v5, v4, 4, v5
	v_add_u32_e32 v221, v3, v5
	v_add_u32_e32 v221, 0x800, v221
	s_lshl_b32 s32, s32, 10
	s_add_i32 s32, s32, 16
	s_branch .LBB0_165

.LBB0_225:
	v_add_f32_e32 v68, v68, v69
	v_fmac_f32_e32 v68, v35, v128
	s_cmp_eq_u32 s73, 3
	s_waitcnt lgkmcnt(0)
	s_barrier
	s_cbranch_scc1 .LBB0_254
	s_cmp_gt_u32 s73, 4
	s_cselect_b64 s[8:9], -1, 0
	s_cmp_lt_u32 s73, 5
	s_cbranch_scc1 .LBB0_228
	v_sub_u32_e64 v35, s24, 4 clamp
	v_lshlrev_b32_e32 v35, 6, v35
	v_add_u32_e32 v52, s25, v35
	v_ashrrev_i32_e32 v53, 31, v52
	v_lshl_add_u64 v[52:53], v[52:53], 0, v[114:115]
	v_lshlrev_b64 v[52:53], 13, v[52:53]
	v_lshl_add_u64 v[54:55], v[124:125], 0, v[52:53]
	v_lshl_add_u64 v[52:53], v[126:127], 0, v[52:53]
	global_load_dwordx4 v[100:103], v[54:55], off
	global_load_dwordx4 v[104:107], v[52:53], off
	s_mov_b32 s40, 1
	s_add_i32 s41, s24, s40
	s_add_i32 s41, s41, -4
	s_max_i32 s41, s41, 0
	s_min_i32 s41, s41, 0x7f
	s_lshl_b32 s41, s41, 6
	s_add_i32 s41, s41, s25
	s_lshl_b32 s41, s41, 13
	s_and_b32 s38, s2, 15
	s_lshl_b32 s38, s38, 7
	s_add_u32 s38, s27, s38
	s_addc_u32 s39, s28, 0
	s_add_u32 s38, s38, s41
	s_addc_u32 s39, s39, 0
	s_and_b32 s40, s40, 3
	s_lshl_b32 s40, s40, 2
	s_lshr_b32 s40, 0x1650, s40
	s_and_b32 s40, s40, 15
	s_lshl_b32 s40, s40, 13
	s_add_i32 s40, s40, s32
	s_mov_b32 m0, s40
	s_nop 0
	global_load_lds_dwordx4 v221, s[38:39]
	s_add_i32 m0, s40, 0x4000
	s_nop 0
	global_load_lds_dwordx4 v220, s[38:39]
	s_mov_b32 s40, 2
	s_add_i32 s41, s24, s40
	s_add_i32 s41, s41, -4
	s_max_i32 s41, s41, 0
	s_min_i32 s41, s41, 0x7f
	s_lshl_b32 s41, s41, 6
	s_add_i32 s41, s41, s25
	s_lshl_b32 s41, s41, 13
	s_and_b32 s38, s2, 15
	s_lshl_b32 s38, s38, 7
	s_add_u32 s38, s27, s38
	s_addc_u32 s39, s28, 0
	s_add_u32 s38, s38, s41
	s_addc_u32 s39, s39, 0
	s_and_b32 s40, s40, 3
	s_lshl_b32 s40, s40, 2
	s_lshr_b32 s40, 0x1650, s40
	s_and_b32 s40, s40, 15
	s_lshl_b32 s40, s40, 13
	s_add_i32 s40, s40, s32
	s_mov_b32 m0, s40
	s_nop 0
	global_load_lds_dwordx4 v221, s[38:39]
	s_add_i32 m0, s40, 0x4000
	s_nop 0
	global_load_lds_dwordx4 v220, s[38:39]

.LBB0_233:
	ds_read_b64_tr_b16 v[54:55], v139 offset:0
	ds_read_b64_tr_b16 v[56:57], v139 offset:0x400
	ds_read_b64_tr_b16 v[58:59], v139 offset:0x800
	ds_read_b64_tr_b16 v[60:61], v139 offset:0xc00
	ds_read_b64_tr_b16 v[62:63], v139 offset:0x1000
	ds_read_b64_tr_b16 v[64:65], v139 offset:0x1400
	ds_read_b64_tr_b16 v[70:71], v139 offset:0x1800
	ds_read_b64_tr_b16 v[72:73], v139 offset:0x1c00
	s_nop 0
	s_waitcnt lgkmcnt(6)
	v_mfma_f32_32x32x16_bf16 v[2:17], v[48:51], v[54:57], v[2:17]
	ds_read_b64_tr_b16 v[54:55], v139 offset:0x200
	ds_read_b64_tr_b16 v[56:57], v139 offset:0x600
	s_waitcnt lgkmcnt(6)
	v_mfma_f32_32x32x16_bf16 v[2:17], v[44:47], v[58:61], v[2:17]
	ds_read_b64_tr_b16 v[58:59], v139 offset:0xa00
	ds_read_b64_tr_b16 v[60:61], v139 offset:0xe00
	s_waitcnt lgkmcnt(6)
	v_mfma_f32_32x32x16_bf16 v[2:17], v[40:43], v[62:65], v[2:17]
	ds_read_b64_tr_b16 v[62:63], v139 offset:0x1200
	ds_read_b64_tr_b16 v[64:65], v139 offset:0x1600
	s_waitcnt lgkmcnt(6)
	v_mfma_f32_32x32x16_bf16 v[2:17], v[36:39], v[70:73], v[2:17]
	ds_read_b64_tr_b16 v[70:71], v139 offset:0x1a00
	ds_read_b64_tr_b16 v[72:73], v139 offset:0x1e00
	s_waitcnt lgkmcnt(6)
	v_mfma_f32_32x32x16_bf16 v[18:33], v[48:51], v[54:57], v[18:33]
	s_andn2_b64 vcc, exec, s[8:9]
	s_waitcnt lgkmcnt(4)
	v_mfma_f32_32x32x16_bf16 v[18:33], v[44:47], v[58:61], v[18:33]
	s_waitcnt lgkmcnt(2)
	v_mfma_f32_32x32x16_bf16 v[18:33], v[40:43], v[62:65], v[18:33]
	s_waitcnt lgkmcnt(0)
	v_mfma_f32_32x32x16_bf16 v[18:33], v[36:39], v[70:73], v[18:33]
	s_cbranch_vccnz .LBB0_235
	s_waitcnt vmcnt(4)
	ds_write_b128 v113, v[104:107]
	ds_write_b128 v117, v[100:103] offset:16384

.LBB0_238:
	s_cmp_gt_u32 s39, 8
	s_cbranch_scc1 .Lna_nodma
	s_add_i32 s40, s39, 3
	s_add_i32 s41, s24, s40
	s_add_i32 s41, s41, -4
	s_max_i32 s41, s41, 0
	s_min_i32 s41, s41, 0x7f
	s_lshl_b32 s41, s41, 6
	s_add_i32 s41, s41, s25
	s_lshl_b32 s41, s41, 13
	s_and_b32 s8, s2, 15
	s_lshl_b32 s8, s8, 7
	s_add_u32 s8, s27, s8
	s_addc_u32 s9, s28, 0
	s_add_u32 s8, s8, s41
	s_addc_u32 s9, s9, 0
	s_and_b32 s40, s40, 3
	s_lshl_b32 s40, s40, 2
	s_lshr_b32 s40, 0x1650, s40
	s_and_b32 s40, s40, 15
	s_lshl_b32 s40, s40, 13
	s_add_i32 s40, s40, s32
	s_mov_b32 m0, s40
	s_nop 0
	global_load_lds_dwordx4 v221, s[8:9]
	s_add_i32 m0, s40, 0x4000
	s_nop 0
	global_load_lds_dwordx4 v220, s[8:9]
.Lna_nodma:
	s_add_i32 s41, s24, s39
.LBB0_242:
	s_add_i32 s40, s39, 4
	s_and_b32 s40, s40, 1
	s_add_i32 s41, s41, -4
	v_cmp_ge_i32_e32 vcc, s41, v173
	v_cmp_lt_i32_e64 s[74:75], s41, v174
	s_and_b64 vcc, vcc, s[74:75]
	s_and_saveexec_b64 s[74:75], vcc
	s_cbranch_execz .LBB0_249
	s_and_b32 s41, s39, 3
	s_lshl_b32 s41, s41, 2
	s_lshr_b32 s41, 0x1650, s41
	s_and_b32 s41, s41, 15
	s_lshl_b32 s41, s41, 13
	v_add_u32_e32 v82, s41, v136
	v_add_u32_e32 v50, v82, v130
	ds_read_b128 v[66:69], v50 offset:16384
	ds_read_b128 v[180:183], v50 offset:20480
	v_add_u32_e32 v83, v82, v131
	v_add_u32_e32 v128, v175, v169
	v_readlane_b32 vcc_lo, v254, 22
	s_waitcnt lgkmcnt(1)
	v_mfma_f32_32x32x16_bf16 v[50:65], v[66:69], v[84:87], v[34:49]
	v_readlane_b32 vcc_hi, v254, 23
	s_waitcnt lgkmcnt(0)
	v_mfma_f32_32x32x16_bf16 v[66:81], v[180:183], v[84:87], v[34:49]
	ds_read_b128 v[180:183], v83 offset:16384
	ds_read_b128 v[184:187], v83 offset:20480
	v_add_u32_e32 v83, v82, v132
	v_add_u32_e32 v82, v82, v133
	s_waitcnt lgkmcnt(0)
	v_mfma_f32_32x32x16_bf16 v[66:81], v[184:187], v[88:91], v[66:81]
	v_mfma_f32_32x32x16_bf16 v[50:65], v[180:183], v[88:91], v[50:65]
	ds_read_b128 v[180:183], v83 offset:16384
	ds_read_b128 v[184:187], v83 offset:20480
	v_add_u32_e32 v83, v175, v171
	s_waitcnt lgkmcnt(0)
	v_mfma_f32_32x32x16_bf16 v[66:81], v[184:187], v[92:95], v[66:81]
	v_mfma_f32_32x32x16_bf16 v[50:65], v[180:183], v[92:95], v[50:65]
	ds_read_b128 v[180:183], v82 offset:16384
	ds_read_b128 v[184:187], v82 offset:20480
	v_add_u32_e32 v82, v175, v172
	ds_read_b32 v82, v82 offset:35260
	ds_read_b32 v83, v83 offset:35260
	ds_read_b32 v128, v128 offset:35260
	s_waitcnt lgkmcnt(3)
	v_mfma_f32_32x32x16_bf16 v[66:81], v[184:187], v[96:99], v[66:81]
	v_mfma_f32_32x32x16_bf16 v[50:65], v[180:183], v[96:99], v[50:65]
	s_waitcnt lgkmcnt(1)
	s_nop 9
	v_add_f32_e32 v66, v66, v83
	v_add_u32_e32 v83, v175, v170
	ds_read_b32 v83, v83 offset:35260
	v_cndmask_b32_e32 v66, v218, v66, vcc
	v_readlane_b32 vcc_lo, v254, 26
	v_readlane_b32 vcc_hi, v254, 27
	s_waitcnt lgkmcnt(0)
	v_pk_add_f32 v[82:83], v[50:51], v[82:83]
	s_nop 0
	v_cndmask_b32_e32 v51, v82, v218, vcc
	v_readlane_b32 vcc_lo, v254, 24
	v_readlane_b32 vcc_hi, v254, 25
	v_add_f32_e32 v50, v67, v128
	s_nop 0
	v_cndmask_b32_e32 v82, v83, v218, vcc
	v_readlane_b32 vcc_lo, v254, 28
	v_readlane_b32 vcc_hi, v254, 29
	s_nop 1
	v_cndmask_b32_e32 v67, v218, v50, vcc
	v_add_u32_e32 v50, v175, v168
	ds_read_b32 v128, v50 offset:35260
	v_add_u32_e32 v50, v175, v167
	ds_read_b32 v50, v50 offset:35260
	v_readlane_b32 vcc_lo, v254, 30
	v_readlane_b32 vcc_hi, v254, 31
	s_waitcnt lgkmcnt(0)
	v_add_f32_e32 v50, v68, v50
	v_cndmask_b32_e32 v68, v218, v50, vcc
	v_add_u32_e32 v50, v175, v166
	ds_read_b32 v129, v50 offset:35260
	v_add_u32_e32 v50, v175, v165
	ds_read_b32 v50, v50 offset:35260
	v_readlane_b32 vcc_lo, v254, 34
	v_readlane_b32 vcc_hi, v254, 35
	s_waitcnt lgkmcnt(1)
	v_pk_add_f32 v[52:53], v[52:53], v[128:129]
	s_waitcnt lgkmcnt(0)
	v_add_f32_e32 v50, v69, v50
	v_cndmask_b32_e32 v83, v52, v218, vcc
	v_readlane_b32 vcc_lo, v254, 32
	v_readlane_b32 vcc_hi, v254, 33
	s_nop 1
	v_cndmask_b32_e32 v128, v53, v218, vcc
	v_readlane_b32 vcc_lo, v254, 36
	v_readlane_b32 vcc_hi, v254, 37
	s_nop 1
	v_cndmask_b32_e32 v69, v218, v50, vcc
	v_add_u32_e32 v50, v175, v164
	ds_read_b32 v180, v50 offset:35260
	v_add_u32_e32 v50, v175, v163
	ds_read_b32 v50, v50 offset:35260
	v_readlane_b32 vcc_lo, v254, 38
	v_readlane_b32 vcc_hi, v254, 39
	s_waitcnt lgkmcnt(0)
	v_add_f32_e32 v50, v70, v50
	v_cndmask_b32_e32 v52, v218, v50, vcc
	v_add_u32_e32 v50, v175, v162
	ds_read_b32 v181, v50 offset:35260
	v_add_u32_e32 v50, v175, v161
	ds_read_b32 v50, v50 offset:35260
	v_readlane_b32 vcc_lo, v254, 42
	v_readlane_b32 vcc_hi, v254, 43
	s_waitcnt lgkmcnt(1)
	v_pk_add_f32 v[54:55], v[54:55], v[180:181]
	s_waitcnt lgkmcnt(0)
	v_add_f32_e32 v50, v71, v50
	v_cndmask_b32_e32 v129, v54, v218, vcc
	v_readlane_b32 vcc_lo, v254, 40
	v_readlane_b32 vcc_hi, v254, 41
	s_nop 1
	v_cndmask_b32_e32 v54, v55, v218, vcc
	v_readlane_b32 vcc_lo, v254, 44
	v_readlane_b32 vcc_hi, v254, 45
	s_nop 1
	v_cndmask_b32_e32 v53, v218, v50, vcc
	v_add_u32_e32 v50, v175, v160
	ds_read_b32 v180, v50 offset:35260
	v_add_u32_e32 v50, v175, v159
	ds_read_b32 v50, v50 offset:35260
	v_readlane_b32 vcc_lo, v254, 46
	v_readlane_b32 vcc_hi, v254, 47
	s_waitcnt lgkmcnt(0)
	v_add_f32_e32 v50, v72, v50
	v_cndmask_b32_e32 v70, v218, v50, vcc
	v_add_u32_e32 v50, v175, v158
	ds_read_b32 v181, v50 offset:35260
	v_add_u32_e32 v50, v175, v157
	ds_read_b32 v50, v50 offset:35260
	v_readlane_b32 vcc_lo, v254, 50
	v_readlane_b32 vcc_hi, v254, 51
	s_waitcnt lgkmcnt(1)
	v_pk_add_f32 v[56:57], v[56:57], v[180:181]
	s_nop 0
	v_cndmask_b32_e32 v55, v56, v218, vcc
	v_readlane_b32 vcc_lo, v254, 48
	v_readlane_b32 vcc_hi, v254, 49
	s_nop 1
	v_cndmask_b32_e32 v56, v57, v218, vcc
	v_readlane_b32 vcc_lo, v254, 52
	v_add_u32_e32 v57, v175, v155
	v_readlane_b32 vcc_hi, v254, 53
	ds_read_b32 v180, v57 offset:35260
	s_waitcnt lgkmcnt(1)
	v_add_f32_e32 v50, v73, v50
	v_cndmask_b32_e32 v71, v218, v50, vcc
	v_add_u32_e32 v50, v175, v156
	ds_read_b32 v50, v50 offset:35260
	v_readlane_b32 vcc_lo, v254, 54
	v_readlane_b32 vcc_hi, v254, 55
	v_add_u32_e32 v73, v175, v151
	s_waitcnt lgkmcnt(0)
	v_add_f32_e32 v50, v58, v50
	v_cndmask_b32_e32 v57, v218, v50, vcc
	v_add_u32_e32 v50, v175, v154
	ds_read_b32 v50, v50 offset:35260
	v_add_u32_e32 v58, v175, v153
	ds_read_b32 v181, v58 offset:35260
	s_waitcnt lgkmcnt(1)
	v_add_f32_e32 v50, v59, v50
	v_cndmask_b32_e64 v72, v218, v50, s[44:45]
	v_add_u32_e32 v50, v175, v152
	ds_read_b32 v50, v50 offset:35260
	s_waitcnt lgkmcnt(1)
	v_pk_add_f32 v[58:59], v[74:75], v[180:181]
	ds_read_b32 v180, v73 offset:35260
	v_add_u32_e32 v75, v175, v147
	v_cndmask_b32_e64 v59, v218, v59, s[10:11]
	s_waitcnt lgkmcnt(1)
	v_add_f32_e32 v50, v60, v50
	v_cndmask_b32_e64 v73, v218, v50, s[50:51]
	v_add_u32_e32 v50, v175, v150
	ds_read_b32 v50, v50 offset:35260
	v_add_u32_e32 v60, v175, v149
	ds_read_b32 v181, v60 offset:35260
	v_cndmask_b32_e64 v58, v218, v58, s[12:13]
	s_waitcnt lgkmcnt(1)
	v_add_f32_e32 v50, v61, v50
	v_cndmask_b32_e64 v74, v218, v50, s[52:53]
	v_add_u32_e32 v50, v175, v148
	ds_read_b32 v50, v50 offset:35260
	s_waitcnt lgkmcnt(1)
	v_pk_add_f32 v[60:61], v[76:77], v[180:181]
	ds_read_b32 v180, v75 offset:35260
	v_add_u32_e32 v77, v175, v143
	v_cndmask_b32_e64 v61, v218, v61, s[14:15]
	s_waitcnt lgkmcnt(1)
	v_add_f32_e32 v50, v62, v50
	v_cndmask_b32_e64 v75, v218, v50, s[58:59]
	v_add_u32_e32 v50, v175, v146
	ds_read_b32 v50, v50 offset:35260
	v_add_u32_e32 v62, v175, v145
	ds_read_b32 v181, v62 offset:35260
	v_cndmask_b32_e64 v60, v218, v60, s[16:17]
	s_waitcnt lgkmcnt(1)
	v_add_f32_e32 v50, v63, v50
	v_cndmask_b32_e64 v76, v218, v50, s[60:61]
	v_add_u32_e32 v50, v175, v144
	ds_read_b32 v50, v50 offset:35260
	s_waitcnt lgkmcnt(1)
	v_pk_add_f32 v[62:63], v[78:79], v[180:181]
	ds_read_b32 v78, v77 offset:35260
	v_cndmask_b32_e64 v63, v218, v63, s[18:19]
	v_cndmask_b32_e64 v62, v218, v62, s[20:21]
	s_waitcnt lgkmcnt(1)
	v_add_f32_e32 v50, v64, v50
	v_add_u32_e32 v64, v175, v142
	v_cndmask_b32_e64 v77, v218, v50, s[66:67]
	s_waitcnt lgkmcnt(0)
	v_add_f32_e32 v50, v80, v78
	ds_read_b32 v64, v64 offset:35260
	v_add_u32_e32 v78, v175, v140
	ds_read_b32 v78, v78 offset:35260
	v_cndmask_b32_e64 v50, v218, v50, s[22:23]
	s_waitcnt lgkmcnt(1)
	v_add_f32_e32 v64, v65, v64
	v_cndmask_b32_e64 v65, v218, v64, s[70:71]
	s_waitcnt lgkmcnt(0)
	v_add_f32_e32 v64, v81, v78
	v_max_f32_e32 v78, v51, v82
	v_max3_f32 v78, v78, v83, v128
	v_max3_f32 v78, v78, v129, v54
	v_max3_f32 v78, v78, v55, v56
	v_max3_f32 v78, v78, v57, v72
	v_max3_f32 v78, v78, v73, v74
	v_max3_f32 v78, v78, v75, v76
	v_max3_f32 v78, v78, v77, v65
	v_max3_f32 v78, v78, v66, v67
	v_max3_f32 v78, v78, v68, v69
	v_max3_f32 v78, v78, v52, v53
	v_max3_f32 v78, v78, v70, v71
	v_max3_f32 v78, v78, v58, v59
	v_max3_f32 v78, v78, v60, v61
	v_cndmask_b32_e64 v64, v218, v64, s[30:31]
	v_max3_f32 v78, v78, v62, v63
	v_max3_f32 v78, v78, v50, v64
	v_mov_b32_e32 v79, v78
	s_nop 1
	v_permlane32_swap_b32_e32 v78, v79
	v_max_f32_e32 v79, v79, v79
	v_max_f32_e32 v78, v78, v78
	v_max_f32_e32 v79, v78, v79
	v_cmp_ge_f32_e32 vcc, s64, v79
	v_mov_b32_e32 v78, 1.0
	s_cmp_eq_u64 vcc, exec
	s_cbranch_scc0 .LBB0_251

.LBB0_249:
	s_or_b64 exec, exec, s[74:75]
	s_sub_i32 s8, s38, s39
	s_cmp_gt_u32 s8, 3
	s_cbranch_scc1 .Lna_w4
	s_cmp_eq_u32 s8, 3
	s_cbranch_scc1 .Lna_w2
	s_waitcnt vmcnt(0)
	s_branch .LBB0_237
.Lna_w2:
	s_waitcnt vmcnt(2)
	s_branch .LBB0_237
.Lna_w4:
	s_waitcnt vmcnt(4)
	s_branch .LBB0_237
